# attention: V-tile DMA issued behind the last QK MFMA of each half-step (lands during PV/softmax instead of during the QK K-fragment reads)
# baseline (speedup 1.0000x reference)
; __device__ __forceinline__ void finishSM(f32x16& p0, f32x16& p1, float alpha, float& l_reg, bf16x8& pa0, bf16x8& pa1, bf16x8& pa2, bf16x8& pa3) {
;     for (int r = 0; r < 16; ++r) p1[r] = __builtin_amdgcn_exp2f(p1[r]);
;     float ps = 0; for (int r = 0; r < 16; ++r) ps += p0[r]; for (int r = 0; r < 16; ++r) ps += p1[r];
;     { auto rr = __builtin_amdgcn_permlane32_swap(__float_as_uint(ps), __float_as_uint(ps), false, false);
;       ps = __uint_as_float(rr[0]) + __uint_as_float(rr[1]); }
;     l_reg = l_reg * alpha + ps;
;     ...
;     PK4(p0, 0, pa0); PK4(p0, 8, pa1); PK4(p1, 0, pa2); PK4(p1, 8, pa3);
;     ...
; }
; template <int KB>
; __device__ __forceinline__ void qkt(f32x16& p0, f32x16& p1, const char* K_lds, int r32, int hi, const bf16x8* qr) {
;     p0 = f32x16{}; p1 = f32x16{};
;     const char* kb[4];
; #pragma unroll
;     for (int dd = 0; dd < 4; ++dd) kb[dd] = K_lds + KB * SHM_K + KSWZ(r32, (dd * 16 + hi * 8) * 2);
; #pragma unroll
;     for (int d0 = 0; d0 < 8; ++d0) { const char* a = kb[d0 & 3] + (d0 >> 2) * 128;
;         bf16x8 b0 = *reinterpret_cast<const bf16x8*>(a);
;         bf16x8 b1 = *reinterpret_cast<const bf16x8*>(a + 32 * 256);
;         p0 = __builtin_amdgcn_mfma_f32_32x32x16_bf16(b0, qr[d0], p0, 0, 0, 0);
;         p1 = __builtin_amdgcn_mfma_f32_32x32x16_bf16(b1, qr[d0], p1, 0, 0, 0); }
; }
.LBB0_89:
	ds_read_b128 v[66:69], v169 offset:49152
	ds_read_b128 v[70:73], v169 offset:57344
	ds_read_b128 v[100:103], v193 offset:49152
	ds_read_b128 v[136:139], v193 offset:57344
	v_add_f32_e32 v148, 0, v231
	v_add_f32_e32 v148, v233, v148
	v_add_f32_e32 v148, v229, v148
	v_add_f32_e32 v148, v232, v148
	v_add_f32_e32 v148, v228, v148
	v_add_f32_e32 v148, v230, v148
	v_add_f32_e32 v148, v226, v148
	v_add_f32_e32 v148, v227, v148
	v_add_f32_e32 v148, v223, v148
	v_add_f32_e32 v148, v225, v148
	v_add_f32_e32 v148, v209, v148
	v_add_f32_e32 v148, v224, v148
	v_add_f32_e32 v148, v206, v148
	v_add_f32_e32 v148, v208, v148
	v_add_f32_e32 v148, v205, v148
	v_add_f32_e32 v148, v207, v148
	v_exp_f32_e32 v140, v152
	v_exp_f32_e32 v141, v153
	v_exp_f32_e32 v142, v180
	v_exp_f32_e32 v143, v181
	s_waitcnt lgkmcnt(3)
	v_mfma_f32_32x32x16_bf16 v[82:97], v[66:69], v[132:135], 0
	v_exp_f32_e32 v144, v160
	v_exp_f32_e32 v145, v161
	v_exp_f32_e32 v146, v154
	v_exp_f32_e32 v147, v155
	s_waitcnt lgkmcnt(2)
	v_mfma_f32_32x32x16_bf16 v[66:81], v[70:73], v[132:135], 0
	v_exp_f32_e32 v178, v178
	v_exp_f32_e32 v179, v179
	v_exp_f32_e32 v162, v162
	v_exp_f32_e32 v163, v163
	s_waitcnt lgkmcnt(1)
	v_mfma_f32_32x32x16_bf16 v[82:97], v[100:103], v[128:131], v[82:97]
	v_add_f32_e32 v148, v178, v148
	v_add_f32_e32 v148, v179, v148
	v_add_f32_e32 v148, v162, v148
	v_exp_f32_e32 v158, v158
	s_waitcnt lgkmcnt(0)
	v_mfma_f32_32x32x16_bf16 v[66:81], v[136:139], v[128:131], v[66:81]
	v_exp_f32_e32 v159, v159
	v_exp_f32_e32 v156, v156
	v_exp_f32_e32 v157, v157
	v_add_f32_e32 v148, v163, v148
	ds_read_b128 v[100:103], v194 offset:49152
	ds_read_b128 v[136:139], v194 offset:57344
	s_waitcnt lgkmcnt(1)
	v_mfma_f32_32x32x16_bf16 v[82:97], v[100:103], v[124:127], v[82:97]
	v_add_f32_e32 v148, v158, v148
	v_add_f32_e32 v148, v159, v148
	v_add_f32_e32 v148, v156, v148
	v_add_f32_e32 v148, v157, v148
	s_waitcnt lgkmcnt(0)
	v_mfma_f32_32x32x16_bf16 v[66:81], v[136:139], v[124:127], v[66:81]
	v_add_f32_e32 v148, v140, v148
	v_add_f32_e32 v148, v141, v148
	v_add_f32_e32 v148, v142, v148
	v_add_f32_e32 v148, v143, v148
	ds_read_b128 v[100:103], v195 offset:49152
	ds_read_b128 v[136:139], v195 offset:57344
	s_waitcnt lgkmcnt(1)
	v_mfma_f32_32x32x16_bf16 v[82:97], v[100:103], v[120:123], v[82:97]
	v_add_f32_e32 v148, v144, v148
	v_add_f32_e32 v148, v145, v148
	v_add_f32_e32 v148, v146, v148
	v_add_f32_e32 v199, v147, v148
	s_waitcnt lgkmcnt(0)
	v_mfma_f32_32x32x16_bf16 v[66:81], v[136:139], v[120:123], v[66:81]
	v_mov_b32_e32 v200, v199
	s_nop 1
	v_permlane32_swap_b32_e32 v199, v200
	v_cvt_pk_bf16_f32 v148, v231, v233
	v_cvt_pk_bf16_f32 v149, v229, v232
	v_cvt_pk_bf16_f32 v150, v228, v230
	ds_read_b128 v[100:103], v169 offset:49280
	ds_read_b128 v[136:139], v169 offset:57472
	s_waitcnt lgkmcnt(1)
	v_mfma_f32_32x32x16_bf16 v[82:97], v[100:103], v[116:119], v[82:97]
	v_cvt_pk_bf16_f32 v151, v226, v227
	v_cvt_pk_bf16_f32 v152, v223, v225
	v_cvt_pk_bf16_f32 v153, v209, v224
	s_waitcnt lgkmcnt(0)
	v_mfma_f32_32x32x16_bf16 v[66:81], v[136:139], v[116:119], v[66:81]
	v_cvt_pk_bf16_f32 v154, v206, v208
	v_cvt_pk_bf16_f32 v155, v205, v207
	v_cvt_pk_bf16_f32 v158, v158, v159
	ds_read_b128 v[100:103], v193 offset:49280
	ds_read_b128 v[136:139], v193 offset:57472
	s_waitcnt lgkmcnt(1)
	v_mfma_f32_32x32x16_bf16 v[82:97], v[100:103], v[112:115], v[82:97]
	v_cvt_pk_bf16_f32 v159, v156, v157
	v_cvt_pk_bf16_f32 v156, v178, v179
	v_cvt_pk_bf16_f32 v157, v162, v163
	s_waitcnt lgkmcnt(0)
	v_mfma_f32_32x32x16_bf16 v[66:81], v[136:139], v[112:115], v[66:81]
	v_cvt_pk_bf16_f32 v160, v140, v141
	v_cvt_pk_bf16_f32 v161, v142, v143
	v_cvt_pk_bf16_f32 v162, v144, v145
	ds_read_b128 v[100:103], v194 offset:49280
	ds_read_b128 v[136:139], v194 offset:57472
	s_waitcnt lgkmcnt(1)
	v_mfma_f32_32x32x16_bf16 v[82:97], v[100:103], v[108:111], v[82:97]
	v_cvt_pk_bf16_f32 v163, v146, v147
	s_nop 0
	v_permlane32_swap_b32_e32 v148, v150
	v_permlane32_swap_b32_e32 v149, v151
	s_waitcnt lgkmcnt(0)
	v_mfma_f32_32x32x16_bf16 v[66:81], v[136:139], v[108:111], v[66:81]
	v_permlane32_swap_b32_e32 v152, v154
	v_permlane32_swap_b32_e32 v153, v155
	v_permlane32_swap_b32_e32 v156, v158
	ds_read_b128 v[100:103], v195 offset:49280
	ds_read_b128 v[136:139], v195 offset:57472
	ds_read_b64_tr_b16 v[172:173], v185 offset:0
	ds_read_b64_tr_b16 v[174:175], v185 offset:0x800
	ds_read_b64_tr_b16 v[202:203], v185 offset:0x1000
	ds_read_b64_tr_b16 v[204:205], v185 offset:0x1800
	ds_read_b64_tr_b16 v[206:207], v185 offset:0x2000
	ds_read_b64_tr_b16 v[208:209], v185 offset:0x2800
	ds_read_b64_tr_b16 v[224:225], v185 offset:0x3000
	ds_read_b64_tr_b16 v[226:227], v185 offset:0x3800
	s_waitcnt lgkmcnt(9)
	v_mfma_f32_32x32x16_bf16 v[82:97], v[100:103], v[104:107], v[82:97]
	v_permlane32_swap_b32_e32 v157, v159
	v_permlane32_swap_b32_e32 v160, v162
	v_permlane32_swap_b32_e32 v161, v163
	s_waitcnt lgkmcnt(8)
	v_mfma_f32_32x32x16_bf16 v[66:81], v[136:139], v[104:107], v[66:81]
	s_cmp_eq_u32 s100, 0
	s_cbranch_scc1 .Lmy_hs1_nov
	s_lshl_b32 m0, s32, 1
	s_sub_i32 m0, m0, 0xc000
	s_nop 0
	global_load_lds_dwordx4 v[242:243], off
	s_add_i32 m0, m0, 896
	s_nop 0
	global_load_lds_dwordx4 v[242:243], off offset:128
; __device__ __forceinline__ void mask_tile(f32x16& p0, f32x16& p1, int dq, unsigned W) {
;     const float NEG = -__builtin_inff();
; #pragma unroll
;     for (int r = 0; r < 16; ++r) {
;         const int c = (r & 3) + 8 * (r >> 2);
;         if ((unsigned)(dq - c) >= W) p0[r] = NEG;
;         if ((unsigned)(dq - c - 32) >= W) p1[r] = NEG;
;     }
; }
; template <int VB>
; __device__ __forceinline__ void pv_tile(f32x16* o, int vb0, bf16x8 pa0, bf16x8 pa1, bf16x8 pa2, bf16x8 pa3) {
;     ...
;     PV_D0(0); PV_D0(1); PV_D0(2); PV_D0(3);
;     ...
; }
.Lmy_hs1_nov:
	s_mov_b32 s100, 0
	v_add_u32_e32 v178, s7, v166
	v_add_u32_e32 v100, 1, v178
	v_add_u32_e32 v102, 33, v178
	v_ashrrev_i32_e32 v101, 31, v100
	v_ashrrev_i32_e32 v103, 31, v102
	v_lshlrev_b64 v[140:141], 8, v[100:101]
	v_lshlrev_b64 v[142:143], 8, v[102:103]
	v_lshl_add_u64 v[100:101], v[238:239], 0, v[140:141]
	v_lshl_add_u64 v[140:141], v[234:235], 0, v[140:141]
	v_lshl_add_u64 v[144:145], v[234:235], 0, v[142:143]
	s_nop 0
	s_nop 0
	s_mov_b32 m0, s32
	s_nop 0
	global_load_lds_dwordx4 v[140:141], off
	s_nop 0
	s_add_i32 m0, s32, 0x2000
	s_nop 0
	global_load_lds_dwordx4 v[144:145], off
	s_waitcnt lgkmcnt(0)
	s_nop 0
	v_mfma_f32_32x32x16_bf16 v[50:65], v[148:151], v[172:175], v[50:65]
	ds_read_b64_tr_b16 v[172:173], v185 offset:0x200
	ds_read_b64_tr_b16 v[174:175], v185 offset:0xa00
	v_mfma_f32_32x32x16_bf16 v[50:65], v[152:155], v[202:205], v[50:65]
	ds_read_b64_tr_b16 v[202:203], v185 offset:0x1200
	ds_read_b64_tr_b16 v[204:205], v185 offset:0x1a00
	v_mfma_f32_32x32x16_bf16 v[50:65], v[156:159], v[206:209], v[50:65]
	ds_read_b64_tr_b16 v[206:207], v185 offset:0x2200
	ds_read_b64_tr_b16 v[208:209], v185 offset:0x2a00
	v_mfma_f32_32x32x16_bf16 v[50:65], v[160:163], v[224:227], v[50:65]
	ds_read_b64_tr_b16 v[224:225], v185 offset:0x3200
	ds_read_b64_tr_b16 v[226:227], v185 offset:0x3a00
	s_waitcnt lgkmcnt(0)
	v_mfma_f32_32x32x16_bf16 v[34:49], v[148:151], v[172:175], v[34:49]
	ds_read_b64_tr_b16 v[172:173], v185 offset:0x400
	ds_read_b64_tr_b16 v[174:175], v185 offset:0xc00
	v_mfma_f32_32x32x16_bf16 v[34:49], v[152:155], v[202:205], v[34:49]
	ds_read_b64_tr_b16 v[202:203], v185 offset:0x1400
	ds_read_b64_tr_b16 v[204:205], v185 offset:0x1c00
	v_mfma_f32_32x32x16_bf16 v[34:49], v[156:159], v[206:209], v[34:49]
	ds_read_b64_tr_b16 v[206:207], v185 offset:0x2400
	ds_read_b64_tr_b16 v[208:209], v185 offset:0x2c00
	v_mfma_f32_32x32x16_bf16 v[34:49], v[160:163], v[224:227], v[34:49]
	ds_read_b64_tr_b16 v[224:225], v185 offset:0x3400
	ds_read_b64_tr_b16 v[226:227], v185 offset:0x3c00
	s_waitcnt lgkmcnt(0)
	v_mfma_f32_32x32x16_bf16 v[18:33], v[148:151], v[172:175], v[18:33]
	ds_read_b64_tr_b16 v[172:173], v185 offset:0x600
	ds_read_b64_tr_b16 v[174:175], v185 offset:0xe00
	v_mfma_f32_32x32x16_bf16 v[18:33], v[152:155], v[202:205], v[18:33]
	ds_read_b64_tr_b16 v[202:203], v185 offset:0x1600
	ds_read_b64_tr_b16 v[204:205], v185 offset:0x1e00
	v_mfma_f32_32x32x16_bf16 v[18:33], v[156:159], v[206:209], v[18:33]
	ds_read_b64_tr_b16 v[206:207], v185 offset:0x2600
	ds_read_b64_tr_b16 v[208:209], v185 offset:0x2e00
	v_mfma_f32_32x32x16_bf16 v[18:33], v[160:163], v[224:227], v[18:33]
	ds_read_b64_tr_b16 v[224:225], v185 offset:0x3600
	ds_read_b64_tr_b16 v[226:227], v185 offset:0x3e00
	s_waitcnt lgkmcnt(0)
	v_mfma_f32_32x32x16_bf16 v[2:17], v[148:151], v[172:175], v[2:17]
	s_cmp_le_i32 s7, s6
	v_mfma_f32_32x32x16_bf16 v[2:17], v[152:155], v[202:205], v[2:17]
	v_mfma_f32_32x32x16_bf16 v[2:17], v[156:159], v[206:209], v[2:17]
	v_mfma_f32_32x32x16_bf16 v[2:17], v[160:163], v[224:227], v[2:17]
	s_cbranch_scc1 .LBB0_91
	v_add_u32_e32 v148, 0x4000007b, v197
	v_cmp_gt_u32_e32 vcc, 2.0, v148
	v_add_u32_e32 v148, 0x5b, v197
	s_nop 0
	v_cndmask_b32_e32 v82, v220, v82, vcc
	v_cmp_lt_u32_e32 vcc, s33, v148
	v_add_u32_e32 v148, 0x7a, v197
	s_nop 0
	v_cndmask_b32_e32 v66, v220, v66, vcc
	v_cmp_lt_u32_e32 vcc, s33, v148
	v_add_u32_e32 v148, 0x5a, v197
	s_nop 0
	v_cndmask_b32_e32 v83, v220, v83, vcc
	v_cmp_lt_u32_e32 vcc, s33, v148
	v_add_u32_e32 v148, 0x79, v197
	s_nop 0
	v_cndmask_b32_e32 v67, v220, v67, vcc
	v_cmp_lt_u32_e32 vcc, s33, v148
	v_add_u32_e32 v148, 0x59, v197
	s_nop 0
	v_cndmask_b32_e32 v84, v220, v84, vcc
	v_cmp_lt_u32_e32 vcc, s33, v148
	v_add_u32_e32 v148, 0x78, v197
	s_nop 0
	v_cndmask_b32_e32 v68, v220, v68, vcc
	v_cmp_lt_u32_e32 vcc, s33, v148
	v_add_u32_e32 v148, 0x58, v197
	s_nop 0
	v_cndmask_b32_e32 v85, v220, v85, vcc
	v_cmp_lt_u32_e32 vcc, s33, v148
	v_add_u32_e32 v148, 0x73, v197
	s_nop 0
	v_cndmask_b32_e32 v69, v220, v69, vcc
	v_cmp_lt_u32_e32 vcc, s33, v148
	v_add_u32_e32 v148, 0x53, v197
	s_nop 0
	v_cndmask_b32_e32 v86, v220, v86, vcc
	v_cmp_lt_u32_e32 vcc, s33, v148
	v_add_u32_e32 v148, 0x72, v197
	s_nop 0
	v_cndmask_b32_e32 v70, v220, v70, vcc
	v_cmp_lt_u32_e32 vcc, s33, v148
	v_add_u32_e32 v148, 0x52, v197
	s_nop 0
	v_cndmask_b32_e32 v87, v220, v87, vcc
	v_cmp_lt_u32_e32 vcc, s33, v148
	v_add_u32_e32 v148, 0x71, v197
	s_nop 0
	v_cndmask_b32_e32 v71, v220, v71, vcc
	v_cmp_lt_u32_e32 vcc, s33, v148
	v_add_u32_e32 v148, 0x51, v197
	s_nop 0
	v_cndmask_b32_e32 v88, v220, v88, vcc
	v_cmp_lt_u32_e32 vcc, s33, v148
	v_add_u32_e32 v148, 0x70, v197
	s_nop 0
	v_cndmask_b32_e32 v72, v220, v72, vcc
	v_cmp_lt_u32_e32 vcc, s33, v148
	v_add_u32_e32 v148, 0x50, v197
	s_nop 0
	v_cndmask_b32_e32 v89, v220, v89, vcc
	v_cmp_lt_u32_e32 vcc, s33, v148
	v_add_u32_e32 v148, 0x6b, v197
	s_nop 0
	v_cndmask_b32_e32 v73, v220, v73, vcc
	v_cmp_lt_u32_e32 vcc, s33, v148
	v_add_u32_e32 v148, 0x4b, v197
	s_nop 0
	v_cndmask_b32_e32 v90, v220, v90, vcc
	v_cmp_lt_u32_e32 vcc, s33, v148
	v_add_u32_e32 v148, 0x6a, v197
	s_nop 0
	v_cndmask_b32_e32 v74, v220, v74, vcc
	v_cmp_lt_u32_e32 vcc, s33, v148
	v_add_u32_e32 v148, 0x4a, v197
	s_nop 0
	v_cndmask_b32_e32 v91, v220, v91, vcc
	v_cmp_lt_u32_e32 vcc, s33, v148
	v_add_u32_e32 v148, 0x69, v197
	s_nop 0
	v_cndmask_b32_e32 v75, v220, v75, vcc
	v_cmp_lt_u32_e32 vcc, s33, v148
	v_add_u32_e32 v148, 0x49, v197
	s_nop 0
	v_cndmask_b32_e32 v92, v220, v92, vcc
	v_cmp_lt_u32_e32 vcc, s33, v148
	v_add_u32_e32 v148, 0x68, v197
	s_nop 0
	v_cndmask_b32_e32 v76, v220, v76, vcc
	v_cmp_lt_u32_e32 vcc, s33, v148
	v_add_u32_e32 v148, 0x48, v197
	s_nop 0
	v_cndmask_b32_e32 v93, v220, v93, vcc
	v_cmp_lt_u32_e32 vcc, s33, v148
	v_add_u32_e32 v148, 0x63, v197
	s_nop 0
	v_cndmask_b32_e32 v77, v220, v77, vcc
	v_cmp_lt_u32_e32 vcc, s33, v148
	v_add_u32_e32 v148, 0x43, v197
	s_nop 0
	v_cndmask_b32_e32 v94, v220, v94, vcc
	v_cmp_lt_u32_e32 vcc, s33, v148
	v_add_u32_e32 v148, 0x62, v197
	s_nop 0
	v_cndmask_b32_e32 v78, v220, v78, vcc
	v_cmp_lt_u32_e32 vcc, s33, v148
	v_add_u32_e32 v148, 0x42, v197
	s_nop 0
	v_cndmask_b32_e32 v95, v220, v95, vcc
	v_cmp_lt_u32_e32 vcc, s33, v148
	v_add_u32_e32 v148, 0x61, v197
	s_nop 0
	v_cndmask_b32_e32 v79, v220, v79, vcc
	v_cmp_lt_u32_e32 vcc, s33, v148
	v_add_u32_e32 v148, 0x41, v197
	s_nop 0
	v_cndmask_b32_e32 v96, v220, v96, vcc
	v_cmp_lt_u32_e32 vcc, s33, v148
	v_add_u32_e32 v148, 0x60, v197
	s_nop 0
	v_cndmask_b32_e32 v80, v220, v80, vcc
	v_cmp_lt_u32_e32 vcc, s33, v148
	v_add_u32_e32 v148, 64, v197
	s_nop 0
	v_cndmask_b32_e32 v97, v220, v97, vcc
	v_cmp_lt_u32_e32 vcc, s33, v148
	s_nop 1
	v_cndmask_b32_e32 v81, v220, v81, vcc

; __device__ __forceinline__ void partialSM(f32x16& p0, f32x16& p1, float& m_reg, float& mn, float& alpha, bool rs) {
;     ...
;     constexpr float C2 = 1.4426950408889634f * SCALE;
;     if (__builtin_expect(__all((pmax - m_reg) * SCALE <= THR), 1)) { mn = m_reg; alpha = 1.f; }
;     else { mn = fmaxf(m_reg, pmax); alpha = __builtin_amdgcn_exp2f((m_reg - mn) * C2); m_reg = mn; }
;     const float mnL = rs ? -mn * C2 : -__builtin_inff();
;     for (int r = 0; r < 16; ++r) p0[r] = fmaf(p0[r], C2, mnL); for (int r = 0; r < 16; ++r) p1[r] = fmaf(p1[r], C2, mnL);
;     for (int r = 0; r < 16; ++r) p0[r] = __builtin_amdgcn_exp2f(p0[r]);
; }
.LBB0_95:
	v_cndmask_b32_e64 v179, v148, v198, s[42:43]
	v_mul_f32_e32 v148, 0xbe0293ee, v179
	v_cndmask_b32_e64 v180, v220, v148, s[40:41]
	v_fmamk_f32 v82, v82, 0x3e0293ee, v180
	v_fmamk_f32 v83, v83, 0x3e0293ee, v180
	v_fmamk_f32 v84, v84, 0x3e0293ee, v180
	v_fmamk_f32 v85, v85, 0x3e0293ee, v180
	v_fmamk_f32 v86, v86, 0x3e0293ee, v180
	v_fmamk_f32 v87, v87, 0x3e0293ee, v180
	v_fmamk_f32 v88, v88, 0x3e0293ee, v180
	v_fmamk_f32 v89, v89, 0x3e0293ee, v180
	v_fmamk_f32 v90, v90, 0x3e0293ee, v180
	v_fmamk_f32 v91, v91, 0x3e0293ee, v180
	v_fmamk_f32 v92, v92, 0x3e0293ee, v180
	v_fmamk_f32 v93, v93, 0x3e0293ee, v180
	v_fmamk_f32 v94, v94, 0x3e0293ee, v180
	v_fmamk_f32 v95, v95, 0x3e0293ee, v180
	v_fmamk_f32 v96, v96, 0x3e0293ee, v180
	v_fmamk_f32 v97, v97, 0x3e0293ee, v180
	v_exp_f32_e32 v148, v82
	v_exp_f32_e32 v163, v83
	v_exp_f32_e32 v149, v84
	v_exp_f32_e32 v162, v85
	v_exp_f32_e32 v150, v86
	v_exp_f32_e32 v161, v87
	v_exp_f32_e32 v151, v88
	v_exp_f32_e32 v160, v89
	v_exp_f32_e32 v152, v90
	v_exp_f32_e32 v159, v91
	v_exp_f32_e32 v153, v92
	v_exp_f32_e32 v158, v93
	v_exp_f32_e32 v154, v94
	v_exp_f32_e32 v157, v95
	v_exp_f32_e32 v155, v96
	v_exp_f32_e32 v156, v97
	v_fmamk_f32 v203, v73, 0x3e0293ee, v180
	v_fmamk_f32 v204, v74, 0x3e0293ee, v180
	v_fmamk_f32 v208, v66, 0x3e0293ee, v180
	v_fmamk_f32 v209, v67, 0x3e0293ee, v180
	v_fmamk_f32 v223, v68, 0x3e0293ee, v180
	v_fmamk_f32 v224, v69, 0x3e0293ee, v180
	v_fmamk_f32 v225, v70, 0x3e0293ee, v180
	v_fmamk_f32 v198, v71, 0x3e0293ee, v180
	v_fmamk_f32 v201, v72, 0x3e0293ee, v180
	v_fmamk_f32 v205, v75, 0x3e0293ee, v180
	v_fmamk_f32 v206, v76, 0x3e0293ee, v180
	v_fmamk_f32 v207, v77, 0x3e0293ee, v180
	v_fmamk_f32 v181, v78, 0x3e0293ee, v180
	v_fmamk_f32 v226, v79, 0x3e0293ee, v180
	v_fmamk_f32 v227, v80, 0x3e0293ee, v180
	v_fmac_f32_e32 v180, 0x3e0293ee, v81
	s_waitcnt lgkmcnt(0)
	s_barrier
; __device__ __forceinline__ void finishSM(f32x16& p0, f32x16& p1, float alpha, float& l_reg, bf16x8& pa0, bf16x8& pa1, bf16x8& pa2, bf16x8& pa3) {
;     for (int r = 0; r < 16; ++r) p1[r] = __builtin_amdgcn_exp2f(p1[r]);
;     float ps = 0; for (int r = 0; r < 16; ++r) ps += p0[r]; for (int r = 0; r < 16; ++r) ps += p1[r];
;     { auto rr = __builtin_amdgcn_permlane32_swap(__float_as_uint(ps), __float_as_uint(ps), false, false);
;       ps = __uint_as_float(rr[0]) + __uint_as_float(rr[1]); }
;     l_reg = l_reg * alpha + ps;
;     ...
;     PK4(p0, 0, pa0); PK4(p0, 8, pa1); PK4(p1, 0, pa2); PK4(p1, 8, pa3);
;     ...
; }
; template <int KB>
; __device__ __forceinline__ void qkt(f32x16& p0, f32x16& p1, const char* K_lds, int r32, int hi, const bf16x8* qr) {
;     p0 = f32x16{}; p1 = f32x16{};
;     const char* kb[4];
; #pragma unroll
;     for (int dd = 0; dd < 4; ++dd) kb[dd] = K_lds + KB * SHM_K + KSWZ(r32, (dd * 16 + hi * 8) * 2);
; #pragma unroll
;     for (int d0 = 0; d0 < 8; ++d0) { const char* a = kb[d0 & 3] + (d0 >> 2) * 128;
;         bf16x8 b0 = *reinterpret_cast<const bf16x8*>(a);
;         bf16x8 b1 = *reinterpret_cast<const bf16x8*>(a + 32 * 256);
;         p0 = __builtin_amdgcn_mfma_f32_32x32x16_bf16(b0, qr[d0], p0, 0, 0, 0);
;         p1 = __builtin_amdgcn_mfma_f32_32x32x16_bf16(b1, qr[d0], p1, 0, 0, 0); }
; }
	ds_read_b128 v[66:69], v169 offset:32768
	ds_read_b128 v[70:73], v169 offset:40960
	ds_read_b128 v[172:175], v193 offset:32768
	ds_read_b128 v[228:231], v193 offset:40960
	v_exp_f32_e32 v198, v198
	v_exp_f32_e32 v201, v201
	v_exp_f32_e32 v214, v204
	v_exp_f32_e32 v205, v205
	v_exp_f32_e32 v206, v206
	v_exp_f32_e32 v207, v207
	v_exp_f32_e32 v181, v181
	v_exp_f32_e32 v215, v226
	v_exp_f32_e32 v216, v227
	v_exp_f32_e32 v180, v180
	v_exp_f32_e32 v218, v209
	v_exp_f32_e32 v209, v203
	v_add_f32_e32 v203, 0, v148
	v_add_f32_e32 v203, v163, v203
	v_add_f32_e32 v203, v149, v203
	v_add_f32_e32 v203, v162, v203
	v_add_f32_e32 v203, v150, v203
	v_add_f32_e32 v203, v161, v203
	v_add_f32_e32 v203, v151, v203
	v_add_f32_e32 v203, v160, v203
	s_waitcnt lgkmcnt(3)
	v_mfma_f32_32x32x16_bf16 v[82:97], v[66:69], v[132:135], 0
	v_add_f32_e32 v203, v152, v203
	v_add_f32_e32 v203, v159, v203
	v_add_f32_e32 v203, v153, v203
	v_add_f32_e32 v203, v158, v203
	s_waitcnt lgkmcnt(2)
	v_mfma_f32_32x32x16_bf16 v[66:81], v[70:73], v[132:135], 0
	v_exp_f32_e32 v217, v208
	v_add_f32_e32 v203, v154, v203
	v_add_f32_e32 v203, v157, v203
	v_exp_f32_e32 v219, v223
	s_waitcnt lgkmcnt(1)
	v_mfma_f32_32x32x16_bf16 v[82:97], v[172:175], v[128:131], v[82:97]
	v_add_f32_e32 v203, v155, v203
	v_exp_f32_e32 v222, v224
	v_add_f32_e32 v203, v156, v203
	v_exp_f32_e32 v208, v225
	s_waitcnt lgkmcnt(0)
	v_mfma_f32_32x32x16_bf16 v[66:81], v[228:231], v[128:131], v[66:81]
	v_add_f32_e32 v203, v217, v203
	v_add_f32_e32 v203, v218, v203
	v_add_f32_e32 v203, v219, v203
	v_add_f32_e32 v203, v222, v203
	ds_read_b128 v[172:175], v194 offset:32768
	ds_read_b128 v[228:231], v194 offset:40960
	s_waitcnt lgkmcnt(1)
	v_mfma_f32_32x32x16_bf16 v[82:97], v[172:175], v[124:127], v[82:97]
	v_add_f32_e32 v203, v208, v203
	v_add_f32_e32 v203, v198, v203
	v_add_f32_e32 v203, v201, v203
	v_add_f32_e32 v203, v209, v203
	s_waitcnt lgkmcnt(0)
	v_mfma_f32_32x32x16_bf16 v[66:81], v[228:231], v[124:127], v[66:81]
	v_add_f32_e32 v203, v214, v203
	v_add_f32_e32 v203, v205, v203
	v_add_f32_e32 v203, v206, v203
	v_add_f32_e32 v203, v207, v203
	ds_read_b128 v[172:175], v195 offset:32768
	ds_read_b128 v[228:231], v195 offset:40960
	s_waitcnt lgkmcnt(1)
	v_mfma_f32_32x32x16_bf16 v[82:97], v[172:175], v[120:123], v[82:97]
	v_add_f32_e32 v203, v181, v203
	v_add_f32_e32 v203, v215, v203
	v_add_f32_e32 v203, v216, v203
	v_add_f32_e32 v203, v180, v203
	s_waitcnt lgkmcnt(0)
	v_mfma_f32_32x32x16_bf16 v[66:81], v[228:231], v[120:123], v[66:81]
	v_mov_b32_e32 v204, v203
	v_cvt_pk_bf16_f32 v148, v148, v163
	v_cvt_pk_bf16_f32 v149, v149, v162
	v_cvt_pk_bf16_f32 v150, v150, v161
	ds_read_b128 v[172:175], v169 offset:32896
	ds_read_b128 v[228:231], v169 offset:41088
	s_waitcnt lgkmcnt(1)
	v_mfma_f32_32x32x16_bf16 v[82:97], v[172:175], v[116:119], v[82:97]
	v_cvt_pk_bf16_f32 v151, v151, v160
	v_cvt_pk_bf16_f32 v152, v152, v159
	v_cvt_pk_bf16_f32 v153, v153, v158
	v_cvt_pk_bf16_f32 v154, v154, v157
	s_waitcnt lgkmcnt(0)
	v_mfma_f32_32x32x16_bf16 v[66:81], v[228:231], v[116:119], v[66:81]
	v_cvt_pk_bf16_f32 v155, v155, v156
	v_cvt_pk_bf16_f32 v156, v217, v218
	v_cvt_pk_bf16_f32 v157, v219, v222
	ds_read_b128 v[172:175], v193 offset:32896
	ds_read_b128 v[228:231], v193 offset:41088
	s_waitcnt lgkmcnt(1)
	v_mfma_f32_32x32x16_bf16 v[82:97], v[172:175], v[112:115], v[82:97]
	v_cvt_pk_bf16_f32 v158, v208, v198
	v_cvt_pk_bf16_f32 v159, v201, v209
	v_cvt_pk_bf16_f32 v160, v214, v205
	s_waitcnt lgkmcnt(0)
	v_mfma_f32_32x32x16_bf16 v[66:81], v[228:231], v[112:115], v[66:81]
	v_cvt_pk_bf16_f32 v161, v206, v207
	v_cvt_pk_bf16_f32 v162, v181, v215
	v_cvt_pk_bf16_f32 v163, v216, v180
	ds_read_b128 v[172:175], v194 offset:32896
	ds_read_b128 v[228:231], v194 offset:41088
	s_waitcnt lgkmcnt(1)
	v_mfma_f32_32x32x16_bf16 v[82:97], v[172:175], v[108:111], v[82:97]
	s_nop 1
	v_permlane32_swap_b32_e32 v203, v204
	v_permlane32_swap_b32_e32 v148, v150
	v_permlane32_swap_b32_e32 v149, v151
	s_waitcnt lgkmcnt(0)
	v_mfma_f32_32x32x16_bf16 v[66:81], v[228:231], v[108:111], v[66:81]
	v_permlane32_swap_b32_e32 v152, v154
	v_permlane32_swap_b32_e32 v153, v155
	v_permlane32_swap_b32_e32 v156, v158
	ds_read_b128 v[172:175], v195 offset:32896
	ds_read_b128 v[228:231], v195 offset:41088
	ds_read_b64_tr_b16 v[206:207], v185 offset:0x5000
	ds_read_b64_tr_b16 v[208:209], v185 offset:0x5800
	ds_read_b64_tr_b16 v[224:225], v185 offset:0x6000
	ds_read_b64_tr_b16 v[226:227], v185 offset:0x6800
	s_waitcnt lgkmcnt(5)
	v_mfma_f32_32x32x16_bf16 v[82:97], v[172:175], v[104:107], v[82:97]
	v_permlane32_swap_b32_e32 v157, v159
	v_permlane32_swap_b32_e32 v160, v162
	v_permlane32_swap_b32_e32 v161, v163
	s_waitcnt lgkmcnt(4)
	v_mfma_f32_32x32x16_bf16 v[66:81], v[228:231], v[104:107], v[66:81]
	s_lshl_b32 m0, s32, 1
	s_sub_i32 m0, m0, 0x10000
	s_nop 0
	global_load_lds_dwordx4 v[100:101], off
	s_add_i32 m0, m0, 896
	s_nop 0
	global_load_lds_dwordx4 v[100:101], off offset:128
	ds_read_b64_tr_b16 v[172:173], v185 offset:0x4000
	ds_read_b64_tr_b16 v[174:175], v185 offset:0x4800
	ds_read_b64_tr_b16 v[228:229], v185 offset:0x7000
	ds_read_b64_tr_b16 v[230:231], v185 offset:0x7800
	s_cmp_lt_u32 s3, s2
	s_cselect_b64 s[22:23], -1, 0
	s_cmp_ge_u32 s3, s2
	s_cbranch_scc1 .LBB0_97
	v_add_u32_e32 v242, 0x41, v178
	v_add_u32_e32 v246, 0x61, v178
	v_ashrrev_i32_e32 v243, 31, v242
	v_ashrrev_i32_e32 v247, 31, v246
	v_lshlrev_b64 v[140:141], 8, v[242:243]
	v_lshlrev_b64 v[142:143], 8, v[246:247]
	v_lshl_add_u64 v[242:243], v[238:239], 0, v[140:141]
	v_lshl_add_u64 v[140:141], v[234:235], 0, v[140:141]
	v_lshl_add_u64 v[144:145], v[234:235], 0, v[142:143]
	s_nop 0
	s_nop 0
	s_add_i32 m0, s32, 0x4000
	s_nop 0
	global_load_lds_dwordx4 v[140:141], off
	s_nop 0
	s_add_i32 m0, s32, 0x6000
	s_nop 0
	global_load_lds_dwordx4 v[144:145], off
	s_mov_b32 s100, 1
